# rg item loops: the barrier closing each item moved to the loop exit (next item's first LDS writes are disjoint and it has its own barrier before touching the shared arrays)
# speedup vs baseline: 1.0074x; 1.0030x over previous
.LBB0_267:
	s_or_b64 exec, exec, s[6:7]
	s_add_i32 s26, s68, s22
	s_add_i32 s70, s11, s88
	s_add_i32 s71, s10, s47
	s_cmpk_gt_i32 s26, 0xfff
	s_cselect_b64 s[8:9], -1, 0
	s_nop 0

.LBB0_350:
	s_or_b64 exec, exec, s[8:9]
	s_mov_b64 s[8:9], -1
	s_cmpk_gt_i32 s68, 0xfff
	v_readfirstlane_b32 s26, v0
	v_readfirstlane_b32 s70, v0
	v_readfirstlane_b32 s71, v0
	s_nop 0
	s_cbranch_scc1 .LBB0_268
	s_add_i32 s8, s89, s69
	s_cmpk_gt_i32 s8, 0xfff
	s_cbranch_scc1 .LBB0_361
	v_mov_b32_e32 v0, v204
	s_add_i32 s8, s88, s11
	v_ashrrev_i32_e32 v2, 3, v0
	v_lshlrev_b32_e32 v0, 3, v0
	s_and_b32 s8, s8, 0x1c0
	v_and_or_b32 v0, v0, 56, s8
	s_add_i32 s8, s47, s10
	s_and_b32 s9, s8, 0xfc0
	v_add_u32_e32 v56, s9, v2
	v_mov_b32_e32 v26, v1
	v_mov_b32_e32 v27, v1
	v_add_u32_e32 v2, -2, v56
	v_lshlrev_b32_e32 v0, 1, v0
	v_mov_b32_e32 v24, 0
	v_mov_b32_e32 v25, v1
	v_mov_b64_e32 v[42:43], v[26:27]
	s_and_b32 s26, s8, 0xfffff000
	v_lshl_add_u64 v[108:109], s[54:55], 0, v[0:1]
	v_cmp_gt_u32_e32 vcc, s1, v2
	v_mov_b64_e32 v[40:41], v[24:25]
	s_and_saveexec_b64 s[8:9], vcc
	s_cbranch_execz .LBB0_354
	v_or_b32_e32 v0, s26, v2
	v_mad_i64_i32 v[2:3], s[70:71], v0, s46, v[108:109]
	global_load_dwordx4 v[40:43], v[2:3], off

.LBB0_438:
	s_barrier
	s_mov_b64 s[6:7], 0

.LBB0_610:
	s_or_b64 exec, exec, s[6:7]
	v_lshlrev_b32_e32 v153, 14, v153
	v_lshlrev_b32_e32 v154, 2, v154
	v_add3_u32 v153, 0, v153, v154
	v_fmac_f32_e32 v117, v116, v152
	v_lshl_add_u32 v116, v155, 8, v153
	ds_write_b32 v116, v117 offset:58368
	v_fmac_f32_e32 v119, v118, v117
	v_lshl_add_u32 v116, v157, 8, v153
	ds_write_b32 v116, v119 offset:58368
	v_fmac_f32_e32 v121, v120, v119
	v_lshl_add_u32 v116, v158, 8, v153
	ds_write_b32 v116, v121 offset:58368
	v_fmac_f32_e32 v123, v122, v121
	v_lshl_add_u32 v116, v159, 8, v153
	ds_write_b32 v116, v123 offset:58368
	v_fmac_f32_e32 v125, v124, v123
	v_lshl_add_u32 v116, v160, 8, v153
	ds_write_b32 v116, v125 offset:58368
	v_fmac_f32_e32 v127, v126, v125
	v_lshl_add_u32 v116, v161, 8, v153
	ds_write_b32 v116, v127 offset:58368
	v_fmac_f32_e32 v129, v128, v127
	v_lshl_add_u32 v116, v162, 8, v153
	ds_write_b32 v116, v129 offset:58368
	v_fmac_f32_e32 v131, v130, v129
	v_lshl_add_u32 v116, v163, 8, v153
	ds_write_b32 v116, v131 offset:58368
	v_fmac_f32_e32 v133, v132, v131
	v_lshl_add_u32 v116, v164, 8, v153
	ds_write_b32 v116, v133 offset:58368
	v_fmac_f32_e32 v135, v134, v133
	v_lshl_add_u32 v116, v165, 8, v153
	ds_write_b32 v116, v135 offset:58368
	v_fmac_f32_e32 v137, v136, v135
	v_lshl_add_u32 v116, v166, 8, v153
	ds_write_b32 v116, v137 offset:58368
	v_fmac_f32_e32 v139, v138, v137
	v_lshl_add_u32 v116, v167, 8, v153
	ds_write_b32 v116, v139 offset:58368
	v_fmac_f32_e32 v141, v140, v139
	v_lshl_add_u32 v116, v168, 8, v153
	ds_write_b32 v116, v141 offset:58368
	v_fmac_f32_e32 v143, v142, v141
	v_lshl_add_u32 v116, v169, 8, v153
	ds_write_b32 v116, v143 offset:58368
	v_fmac_f32_e32 v145, v144, v143
	v_lshl_add_u32 v116, v170, 8, v153
	ds_write_b32 v116, v145 offset:58368
	v_fmac_f32_e32 v147, v146, v145
	v_lshl_add_u32 v116, v171, 8, v153
	v_lshlrev_b32_e32 v132, 16, v112
	ds_write_b32 v116, v147 offset:58368
	v_mul_f32_e32 v116, 0x3d372713, v132
	v_mul_f32_e32 v116, v116, v132
	v_mov_b32_e32 v117, v132
	v_fmac_f32_e32 v117, v116, v117
	v_mul_f32_e32 v116, 0x3f4c422a, v117
	v_lshlrev_b32_e32 v117, 2, v1
	v_and_b32_e32 v133, 0xffff0000, v112
	v_add3_u32 v128, v151, v117, s46
	v_mul_f32_e32 v117, 0x3d372713, v133
	v_mul_f32_e32 v117, v117, v133
	v_mov_b32_e32 v118, v133
	v_fmac_f32_e32 v118, v117, v118
	v_add_f32_e32 v116, v116, v116
	v_mul_f32_e32 v117, 0x3f4c422a, v118
	v_mul_f32_e32 v116, 0x3fb8aa3b, v116
	v_add_f32_e32 v117, v117, v117
	v_exp_f32_e32 v116, v116
	v_mul_f32_e32 v117, 0x3fb8aa3b, v117
	v_exp_f32_e32 v124, v117
	s_waitcnt lgkmcnt(0)
	v_add_f32_e32 v116, 1.0, v116
	s_barrier
	v_rcp_f32_e32 v134, v116
	ds_read_b128 v[116:119], v3 offset:58368
	ds_read_b128 v[120:123], v128 offset:16384
	v_add_f32_e32 v124, 1.0, v124
	v_rcp_f32_e32 v135, v124
	ds_read_b128 v[124:127], v3 offset:58384
	ds_read_b128 v[128:131], v128 offset:16400
	v_pk_mul_f32 v[132:133], v[132:133], 0.5 op_sel_hi:[1,0]
	s_waitcnt lgkmcnt(2)
	v_pk_add_f32 v[116:117], v[116:117], v[120:121]
	v_pk_fma_f32 v[120:121], v[134:135], 2.0, 1.0 op_sel_hi:[1,0,0] neg_lo:[1,0,0] neg_hi:[1,0,0]
	v_lshlrev_b32_e32 v134, 16, v113
	v_mul_f32_e32 v3, 0x3d372713, v134
	v_mul_f32_e32 v3, v3, v134
	v_mov_b32_e32 v136, v134
	v_and_b32_e32 v135, 0xffff0000, v113
	v_fmac_f32_e32 v136, v3, v136
	v_mul_f32_e32 v3, 0x3f4c422a, v136
	v_mul_f32_e32 v136, 0x3d372713, v135
	v_mul_f32_e32 v136, v136, v135
	v_mov_b32_e32 v137, v135
	v_fmac_f32_e32 v137, v136, v137
	v_add_f32_e32 v3, v3, v3
	v_mul_f32_e32 v136, 0x3f4c422a, v137
	v_mul_f32_e32 v3, 0x3fb8aa3b, v3
	v_add_f32_e32 v136, v136, v136
	v_exp_f32_e32 v3, v3
	v_mul_f32_e32 v136, 0x3fb8aa3b, v136
	v_exp_f32_e32 v137, v136
	v_pk_add_f32 v[120:121], v[120:121], 1.0 op_sel_hi:[1,0]
	v_add_f32_e32 v3, 1.0, v3
	v_rcp_f32_e32 v136, v3
	v_add_f32_e32 v3, 1.0, v137
	v_pk_mul_f32 v[120:121], v[132:133], v[120:121]
	v_lshlrev_b32_e32 v132, 16, v114
	v_rcp_f32_e32 v137, v3
	v_mul_f32_e32 v3, 0x3d372713, v132
	v_pk_add_f32 v[118:119], v[118:119], v[122:123]
	v_pk_mul_f32 v[122:123], v[134:135], 0.5 op_sel_hi:[1,0]
	v_mul_f32_e32 v3, v3, v132
	v_mov_b32_e32 v134, v132
	v_and_b32_e32 v133, 0xffff0000, v114
	v_fmac_f32_e32 v134, v3, v134
	v_mul_f32_e32 v3, 0x3f4c422a, v134
	v_mul_f32_e32 v134, 0x3d372713, v133
	v_mul_f32_e32 v134, v134, v133
	v_mov_b32_e32 v135, v133
	v_fmac_f32_e32 v135, v134, v135
	v_add_f32_e32 v3, v3, v3
	v_mul_f32_e32 v134, 0x3f4c422a, v135
	v_mul_f32_e32 v3, 0x3fb8aa3b, v3
	v_add_f32_e32 v134, v134, v134
	v_exp_f32_e32 v3, v3
	v_mul_f32_e32 v134, 0x3fb8aa3b, v134
	v_exp_f32_e32 v135, v134
	v_pk_mul_f32 v[116:117], v[120:121], v[116:117]
	v_pk_fma_f32 v[120:121], v[136:137], 2.0, 1.0 op_sel_hi:[1,0,0] neg_lo:[1,0,0] neg_hi:[1,0,0]
	v_add_f32_e32 v3, 1.0, v3
	v_pk_add_f32 v[120:121], v[120:121], 1.0 op_sel_hi:[1,0]
	v_rcp_f32_e32 v134, v3
	v_pk_mul_f32 v[120:121], v[122:123], v[120:121]
	v_add_f32_e32 v3, 1.0, v135
	v_pk_mul_f32 v[118:119], v[120:121], v[118:119]
	s_waitcnt lgkmcnt(0)
	v_pk_add_f32 v[120:121], v[124:125], v[128:129]
	v_lshlrev_b32_e32 v128, 16, v115
	v_rcp_f32_e32 v135, v3
	v_mul_f32_e32 v3, 0x3d372713, v128
	v_pk_mul_f32 v[124:125], v[132:133], 0.5 op_sel_hi:[1,0]
	v_mul_f32_e32 v3, v3, v128
	v_mov_b32_e32 v132, v128
	v_and_b32_e32 v129, 0xffff0000, v115
	v_fmac_f32_e32 v132, v3, v132
	v_mul_f32_e32 v3, 0x3f4c422a, v132
	v_mul_f32_e32 v132, 0x3d372713, v129
	v_mul_f32_e32 v132, v132, v129
	v_mov_b32_e32 v133, v129
	v_fmac_f32_e32 v133, v132, v133
	v_add_f32_e32 v3, v3, v3
	v_mul_f32_e32 v132, 0x3f4c422a, v133
	v_mul_f32_e32 v3, 0x3fb8aa3b, v3
	v_add_f32_e32 v132, v132, v132
	v_exp_f32_e32 v3, v3
	v_mul_f32_e32 v132, 0x3fb8aa3b, v132
	v_exp_f32_e32 v133, v132
	s_ashr_i32 s6, s50, 9
	v_add_f32_e32 v3, 1.0, v3
	v_rcp_f32_e32 v132, v3
	v_add_f32_e32 v3, 1.0, v133
	v_rcp_f32_e32 v133, v3
	s_ashr_i32 s7, s6, 31
	s_add_i32 s8, s83, s12
	v_pk_fma_f32 v[122:123], v[134:135], 2.0, 1.0 op_sel_hi:[1,0,0] neg_lo:[1,0,0] neg_hi:[1,0,0]
	s_lshl_b64 s[6:7], s[6:7], 12
	s_and_b32 s8, s8, 0xfc0
	v_pk_add_f32 v[122:123], v[122:123], 1.0 op_sel_hi:[1,0]
	s_or_b32 s6, s6, s8
	v_ashrrev_i32_e32 v3, 31, v2
	v_pk_mul_f32 v[122:123], v[124:125], v[122:123]
	v_pk_fma_f32 v[124:125], v[132:133], 2.0, 1.0 op_sel_hi:[1,0,0] neg_lo:[1,0,0] neg_hi:[1,0,0]
	v_lshl_add_u64 v[2:3], s[6:7], 0, v[2:3]
	s_add_i32 s6, s90, s13
	v_pk_mul_f32 v[120:121], v[122:123], v[120:121]
	v_pk_add_f32 v[122:123], v[126:127], v[130:131]
	v_pk_mul_f32 v[126:127], v[128:129], 0.5 op_sel_hi:[1,0]
	v_pk_add_f32 v[124:125], v[124:125], 1.0 op_sel_hi:[1,0]
	s_and_b32 s6, s6, 0x1c0
	s_add_i32 s2, s50, s22
	v_pk_mul_f32 v[124:125], v[126:127], v[124:125]
	v_or_b32_e32 v1, s6, v1
	v_lshlrev_b64 v[2:3], 11, v[2:3]
	s_add_i32 s13, s13, s88
	s_add_i32 s12, s12, s47
	v_pk_mul_f32 v[122:123], v[124:125], v[122:123]
	v_cvt_pk_bf16_f32 v116, v116, v117
	v_cvt_pk_bf16_f32 v117, v118, v119
	v_cvt_pk_bf16_f32 v118, v120, v121
	v_lshl_add_u64 v[2:3], s[16:17], 0, v[2:3]
	v_lshlrev_b32_e32 v120, 1, v1
	v_mov_b32_e32 v121, v0
	s_cmpk_gt_i32 s2, 0xfff
	v_cvt_pk_bf16_f32 v119, v122, v123
	v_lshl_add_u64 v[2:3], v[2:3], 0, v[120:121]
	s_cselect_b64 s[8:9], -1, 0
	s_waitcnt vmcnt(0)
	global_store_dwordx4 v[2:3], v[116:119], off
	s_nop 0

.LBB0_692:
	s_or_b64 exec, exec, s[8:9]
	v_lshlrev_b32_e32 v153, 14, v153
	v_lshlrev_b32_e32 v154, 2, v154
	v_add3_u32 v153, 0, v153, v154
	v_fmac_f32_e32 v117, v116, v152
	v_lshl_add_u32 v116, v155, 8, v153
	ds_write_b32 v116, v117 offset:58368
	v_fmac_f32_e32 v119, v118, v117
	v_lshl_add_u32 v116, v157, 8, v153
	ds_write_b32 v116, v119 offset:58368
	v_fmac_f32_e32 v121, v120, v119
	v_lshl_add_u32 v116, v158, 8, v153
	ds_write_b32 v116, v121 offset:58368
	v_fmac_f32_e32 v123, v122, v121
	v_lshl_add_u32 v116, v159, 8, v153
	ds_write_b32 v116, v123 offset:58368
	v_fmac_f32_e32 v125, v124, v123
	v_lshl_add_u32 v116, v160, 8, v153
	ds_write_b32 v116, v125 offset:58368
	v_fmac_f32_e32 v127, v126, v125
	v_lshl_add_u32 v116, v161, 8, v153
	ds_write_b32 v116, v127 offset:58368
	v_fmac_f32_e32 v129, v128, v127
	v_lshl_add_u32 v116, v162, 8, v153
	ds_write_b32 v116, v129 offset:58368
	v_fmac_f32_e32 v131, v130, v129
	v_lshl_add_u32 v116, v163, 8, v153
	ds_write_b32 v116, v131 offset:58368
	v_fmac_f32_e32 v133, v132, v131
	v_lshl_add_u32 v116, v164, 8, v153
	ds_write_b32 v116, v133 offset:58368
	v_fmac_f32_e32 v135, v134, v133
	v_lshl_add_u32 v116, v165, 8, v153
	ds_write_b32 v116, v135 offset:58368
	v_fmac_f32_e32 v137, v136, v135
	v_lshl_add_u32 v116, v166, 8, v153
	ds_write_b32 v116, v137 offset:58368
	v_fmac_f32_e32 v139, v138, v137
	v_lshl_add_u32 v116, v167, 8, v153
	ds_write_b32 v116, v139 offset:58368
	v_fmac_f32_e32 v141, v140, v139
	v_lshl_add_u32 v116, v168, 8, v153
	ds_write_b32 v116, v141 offset:58368
	v_fmac_f32_e32 v143, v142, v141
	v_lshl_add_u32 v116, v169, 8, v153
	ds_write_b32 v116, v143 offset:58368
	v_fmac_f32_e32 v145, v144, v143
	v_lshl_add_u32 v116, v170, 8, v153
	ds_write_b32 v116, v145 offset:58368
	v_fmac_f32_e32 v147, v146, v145
	v_lshl_add_u32 v116, v171, 8, v153
	v_lshlrev_b32_e32 v132, 16, v100
	ds_write_b32 v116, v147 offset:58368
	v_mul_f32_e32 v116, 0x3d372713, v132
	v_mul_f32_e32 v116, v116, v132
	v_mov_b32_e32 v117, v132
	v_fmac_f32_e32 v117, v116, v117
	v_mul_f32_e32 v116, 0x3f4c422a, v117
	v_lshlrev_b32_e32 v117, 2, v1
	v_and_b32_e32 v133, 0xffff0000, v100
	v_add3_u32 v128, v151, v117, s46
	v_mul_f32_e32 v117, 0x3d372713, v133
	v_mul_f32_e32 v117, v117, v133
	v_mov_b32_e32 v118, v133
	v_fmac_f32_e32 v118, v117, v118
	v_add_f32_e32 v116, v116, v116
	v_mul_f32_e32 v117, 0x3f4c422a, v118
	v_mul_f32_e32 v116, 0x3fb8aa3b, v116
	v_add_f32_e32 v117, v117, v117
	v_exp_f32_e32 v116, v116
	v_mul_f32_e32 v117, 0x3fb8aa3b, v117
	v_exp_f32_e32 v124, v117
	s_waitcnt lgkmcnt(0)
	v_add_f32_e32 v116, 1.0, v116
	s_barrier
	v_rcp_f32_e32 v134, v116
	ds_read_b128 v[116:119], v3 offset:58368
	ds_read_b128 v[120:123], v128 offset:16384
	v_add_f32_e32 v124, 1.0, v124
	v_rcp_f32_e32 v135, v124
	ds_read_b128 v[124:127], v3 offset:58384
	ds_read_b128 v[128:131], v128 offset:16400
	v_pk_mul_f32 v[132:133], v[132:133], 0.5 op_sel_hi:[1,0]
	s_waitcnt lgkmcnt(2)
	v_pk_add_f32 v[116:117], v[116:117], v[120:121]
	v_pk_fma_f32 v[120:121], v[134:135], 2.0, 1.0 op_sel_hi:[1,0,0] neg_lo:[1,0,0] neg_hi:[1,0,0]
	v_lshlrev_b32_e32 v134, 16, v101
	v_mul_f32_e32 v3, 0x3d372713, v134
	v_mul_f32_e32 v3, v3, v134
	v_mov_b32_e32 v136, v134
	v_and_b32_e32 v135, 0xffff0000, v101
	v_fmac_f32_e32 v136, v3, v136
	v_mul_f32_e32 v3, 0x3f4c422a, v136
	v_mul_f32_e32 v136, 0x3d372713, v135
	v_mul_f32_e32 v136, v136, v135
	v_mov_b32_e32 v137, v135
	v_fmac_f32_e32 v137, v136, v137
	v_add_f32_e32 v3, v3, v3
	v_mul_f32_e32 v136, 0x3f4c422a, v137
	v_mul_f32_e32 v3, 0x3fb8aa3b, v3
	v_add_f32_e32 v136, v136, v136
	v_exp_f32_e32 v3, v3
	v_mul_f32_e32 v136, 0x3fb8aa3b, v136
	v_exp_f32_e32 v137, v136
	v_pk_add_f32 v[120:121], v[120:121], 1.0 op_sel_hi:[1,0]
	v_add_f32_e32 v3, 1.0, v3
	v_rcp_f32_e32 v136, v3
	v_add_f32_e32 v3, 1.0, v137
	v_pk_mul_f32 v[120:121], v[132:133], v[120:121]
	v_lshlrev_b32_e32 v132, 16, v102
	v_rcp_f32_e32 v137, v3
	v_mul_f32_e32 v3, 0x3d372713, v132
	v_pk_add_f32 v[118:119], v[118:119], v[122:123]
	v_pk_mul_f32 v[122:123], v[134:135], 0.5 op_sel_hi:[1,0]
	v_mul_f32_e32 v3, v3, v132
	v_mov_b32_e32 v134, v132
	v_and_b32_e32 v133, 0xffff0000, v102
	v_fmac_f32_e32 v134, v3, v134
	v_mul_f32_e32 v3, 0x3f4c422a, v134
	v_mul_f32_e32 v134, 0x3d372713, v133
	v_mul_f32_e32 v134, v134, v133
	v_mov_b32_e32 v135, v133
	v_fmac_f32_e32 v135, v134, v135
	v_add_f32_e32 v3, v3, v3
	v_mul_f32_e32 v134, 0x3f4c422a, v135
	v_mul_f32_e32 v3, 0x3fb8aa3b, v3
	v_add_f32_e32 v134, v134, v134
	v_exp_f32_e32 v3, v3
	v_mul_f32_e32 v134, 0x3fb8aa3b, v134
	v_exp_f32_e32 v135, v134
	v_pk_mul_f32 v[116:117], v[120:121], v[116:117]
	v_pk_fma_f32 v[120:121], v[136:137], 2.0, 1.0 op_sel_hi:[1,0,0] neg_lo:[1,0,0] neg_hi:[1,0,0]
	v_add_f32_e32 v3, 1.0, v3
	v_pk_add_f32 v[120:121], v[120:121], 1.0 op_sel_hi:[1,0]
	v_rcp_f32_e32 v134, v3
	v_pk_mul_f32 v[120:121], v[122:123], v[120:121]
	v_add_f32_e32 v3, 1.0, v135
	v_pk_mul_f32 v[118:119], v[120:121], v[118:119]
	s_waitcnt lgkmcnt(0)
	v_pk_add_f32 v[120:121], v[124:125], v[128:129]
	v_lshlrev_b32_e32 v128, 16, v103
	v_rcp_f32_e32 v135, v3
	v_mul_f32_e32 v3, 0x3d372713, v128
	v_pk_mul_f32 v[124:125], v[132:133], 0.5 op_sel_hi:[1,0]
	v_mul_f32_e32 v3, v3, v128
	v_mov_b32_e32 v132, v128
	v_and_b32_e32 v129, 0xffff0000, v103
	v_fmac_f32_e32 v132, v3, v132
	v_mul_f32_e32 v3, 0x3f4c422a, v132
	v_mul_f32_e32 v132, 0x3d372713, v129
	v_mul_f32_e32 v132, v132, v129
	v_mov_b32_e32 v133, v129
	v_fmac_f32_e32 v133, v132, v133
	v_add_f32_e32 v3, v3, v3
	v_mul_f32_e32 v132, 0x3f4c422a, v133
	v_mul_f32_e32 v3, 0x3fb8aa3b, v3
	v_add_f32_e32 v132, v132, v132
	v_exp_f32_e32 v3, v3
	v_mul_f32_e32 v132, 0x3fb8aa3b, v132
	v_exp_f32_e32 v133, v132
	s_ashr_i32 s8, s2, 9
	v_add_f32_e32 v3, 1.0, v3
	v_rcp_f32_e32 v132, v3
	v_add_f32_e32 v3, 1.0, v133
	v_rcp_f32_e32 v133, v3
	v_pk_fma_f32 v[122:123], v[134:135], 2.0, 1.0 op_sel_hi:[1,0,0] neg_lo:[1,0,0] neg_hi:[1,0,0]
	s_ashr_i32 s9, s8, 31
	v_pk_add_f32 v[122:123], v[122:123], 1.0 op_sel_hi:[1,0]
	s_lshl_b64 s[8:9], s[8:9], 12
	s_and_b32 s10, s12, 0xfc0
	v_pk_mul_f32 v[122:123], v[124:125], v[122:123]
	v_pk_fma_f32 v[124:125], v[132:133], 2.0, 1.0 op_sel_hi:[1,0,0] neg_lo:[1,0,0] neg_hi:[1,0,0]
	s_or_b32 s8, s8, s10
	v_ashrrev_i32_e32 v3, 31, v2
	v_pk_mul_f32 v[120:121], v[122:123], v[120:121]
	v_pk_add_f32 v[122:123], v[126:127], v[130:131]
	v_pk_mul_f32 v[126:127], v[128:129], 0.5 op_sel_hi:[1,0]
	v_pk_add_f32 v[124:125], v[124:125], 1.0 op_sel_hi:[1,0]
	v_lshl_add_u64 v[2:3], s[8:9], 0, v[2:3]
	s_and_b32 s8, s13, 0x1c0
	v_pk_mul_f32 v[124:125], v[126:127], v[124:125]
	v_or_b32_e32 v1, s8, v1
	v_lshlrev_b64 v[2:3], 11, v[2:3]
	v_pk_mul_f32 v[122:123], v[124:125], v[122:123]
	v_cvt_pk_bf16_f32 v116, v116, v117
	v_cvt_pk_bf16_f32 v117, v118, v119
	v_cvt_pk_bf16_f32 v118, v120, v121
	v_lshl_add_u64 v[2:3], s[16:17], 0, v[2:3]
	v_lshlrev_b32_e32 v120, 1, v1
	v_mov_b32_e32 v121, v0
	v_cvt_pk_bf16_f32 v119, v122, v123
	v_lshl_add_u64 v[2:3], v[2:3], 0, v[120:121]
	s_cmpk_gt_i32 s50, 0xfff
	s_mov_b64 s[8:9], -1
	s_waitcnt vmcnt(0)
	global_store_dwordx4 v[2:3], v[116:119], off
	s_nop 0
	s_cbranch_scc1 .LBB0_611
	s_add_i32 s2, s89, s2
	s_cmpk_gt_i32 s2, 0xfff
	s_cbranch_scc1 .LBB0_703
	v_mov_b32_e32 v118, v204
	s_ashr_i32 s8, s2, 9
	s_bfe_u32 s2, s2, 0x60003
	s_add_i32 s9, s88, s13
	s_and_b32 s61, s9, 0x1c0
	v_ashrrev_i32_e32 v102, 3, v118
	v_lshlrev_b32_e32 v1, 3, v118
	s_lshl_b32 s62, s2, 6
	v_and_or_b32 v2, v1, 56, s61
	v_add_u32_e32 v60, s62, v102
	v_mov_b32_e32 v30, v0
	v_mov_b32_e32 v31, v0
	v_add_u32_e32 v1, -2, v60
	v_lshlrev_b32_e32 v100, 1, v2
	v_mov_b32_e32 v101, v0
	v_mov_b32_e32 v28, v0
	v_mov_b32_e32 v29, v0
	v_mov_b64_e32 v[42:43], v[30:31]
	s_lshl_b32 s9, s8, 12
	v_lshl_add_u64 v[116:117], s[66:67], 0, v[100:101]
	v_cmp_gt_u32_e32 vcc, s48, v1
	v_mov_b64_e32 v[40:41], v[28:29]
	s_and_saveexec_b64 s[10:11], vcc
	s_cbranch_execz .LBB0_696
	v_or_b32_e32 v1, s9, v1
	v_mad_i64_i32 v[2:3], s[64:65], v1, s0, v[116:117]
	global_load_dwordx4 v[40:43], v[2:3], off
